# generation-word sampling also at the top of each attention item for the 5->6 split barrier
# baseline (speedup 1.0000x reference)
.LBB0_907:
	v_mov_b32_e32 v201, 0x24008
	ds_read_b32 v200, v201
	s_add_u32 s98, s34, 0xed10500
	s_addc_u32 s99, s35, 0
	s_waitcnt lgkmcnt(0)
	v_mov_b32_e32 v201, 0
	s_cmp_lt_i32 s88, 7
	s_cselect_b64 s[12:13], -1, 0
	s_and_b64 s[4:5], s[12:13], s[4:5]
	s_andn2_b64 vcc, exec, s[4:5]
	s_cbranch_vccnz .LBB0_960
	s_cmpk_lt_i32 s2, 0x200
	s_cbranch_scc1 .LBB0_910
	s_load_dword s6, s[0:1], 0x120
	s_cbranch_execz .LBB0_911
	s_branch .LBB0_931

.LBB0_912:
	s_and_saveexec_b64 s[100:101], s[92:93]
	global_load_dword v200, v201, s[98:99] sc1
	s_mov_b64 exec, s[100:101]
	s_waitcnt vmcnt(4)
	v_mov_b32_e32 v12, v204
	s_cmpk_gt_i32 s31, 0xff
	s_mov_b64 s[4:5], -1
	s_cbranch_scc0 .LBB0_914
	s_lshl_b32 s4, s31, 4
	s_and_b32 s5, s4, 0x7fffff00
	s_add_i32 s24, s5, 0xfffff000
	s_and_b32 s4, s4, 0x80
	s_or_b32 s6, s24, s4
	s_mov_b64 s[4:5], 0

.LBB0_931:
	s_waitcnt lgkmcnt(0)
	s_cmp_gt_i32 s88, 5
	s_cbranch_scc1 .Lsb_skip
	s_and_saveexec_b64 s[16:17], s[92:93]
	s_cbranch_execz .Lsb_done
	v_mov_b32_e32 v0, 0x24008
	ds_read_b32 v1, v0
	buffer_inv sc1
	s_add_u32 s18, s34, 0xed10500
	s_addc_u32 s19, s35, 0
	v_mov_b32_e32 v0, 0
	s_mov_b32 s20, 0
	s_waitcnt lgkmcnt(0)
	s_waitcnt vmcnt(0)
	v_cmp_eq_u32_e32 vcc, v200, v1
	s_cbranch_vccz .Lsb_done
